# speedup vs baseline: 1.0059x; 1.0059x over previous
.LBB0_408:
	s_waitcnt vmcnt(0)
	s_waitcnt vmcnt(0)
	s_barrier
	s_mov_b64 s[0:1], exec
	v_readlane_b32 s2, v252, 22
	v_readlane_b32 s3, v252, 23
	s_and_b64 s[2:3], s[0:1], s[2:3]
	s_mov_b32 s83, s93
	s_mov_b64 exec, s[2:3]
	s_cbranch_execz .LBB0_460
	v_mov_b32_e32 v4, 0x22000
	ds_read_b32 v5, v4
	ds_read_b32 v6, v4 offset:4
	v_readlane_b32 s3, v252, 21
	s_nop 3
	s_lshl_b32 s3, s3, 8
	s_add_i32 s3, s3, 0x80
	v_mov_b32_e32 v0, s3
	v_mov_b32_e32 v1, 1
	s_add_u32 s4, s60, 0x1400
	s_addc_u32 s5, s61, 0
	global_atomic_add v2, v0, v1, s[4:5] sc0
	s_add_u32 s4, s60, 0x2400
	s_addc_u32 s5, s61, 0
	s_waitcnt vmcnt(0) lgkmcnt(0)
	v_readfirstlane_b32 s2, v2
	v_readfirstlane_b32 s12, v5
	v_readfirstlane_b32 s13, v6
	s_nop 3
	s_mul_i32 s12, s12, 1
	s_mul_i32 s13, s13, 1
	s_add_i32 s2, s2, 1
	s_cmp_lg_u32 s2, s12
	s_cbranch_scc1 .Lmf1_poll
	buffer_wbl2 sc1
	s_waitcnt vmcnt(0)
	v_mov_b32_e32 v3, 0
	s_add_u32 s2, s60, 0x3480
	s_addc_u32 s3, s61, 0
	global_atomic_add v2, v3, v1, s[2:3] sc0
	s_waitcnt vmcnt(0)
	v_readfirstlane_b32 s2, v2
	s_nop 3
	s_add_i32 s2, s2, 1
	s_cmp_lg_u32 s2, s13
	s_cbranch_scc1 .Lmf1_poll
	v_mov_b32_e32 v3, 0x80
	global_atomic_add v3, v1, s[4:5]
	global_atomic_add v3, v1, s[4:5] offset:256
	global_atomic_add v3, v1, s[4:5] offset:512
	global_atomic_add v3, v1, s[4:5] offset:768
	global_atomic_add v3, v1, s[4:5] offset:1024
	global_atomic_add v3, v1, s[4:5] offset:1280
	global_atomic_add v3, v1, s[4:5] offset:1536
	global_atomic_add v3, v1, s[4:5] offset:1792
	global_atomic_add v3, v1, s[4:5] offset:2048
	global_atomic_add v3, v1, s[4:5] offset:2304
	global_atomic_add v3, v1, s[4:5] offset:2560
	global_atomic_add v3, v1, s[4:5] offset:2816
	global_atomic_add v3, v1, s[4:5] offset:3072
	global_atomic_add v3, v1, s[4:5] offset:3328
	global_atomic_add v3, v1, s[4:5] offset:3584
	global_atomic_add v3, v1, s[4:5] offset:3840
.Lmf1_poll:
	s_mov_b32 s3, 0
.Lmf1_pl:
	global_load_dword v2, v0, s[4:5] sc1
	s_waitcnt vmcnt(0)
	v_readfirstlane_b32 s2, v2
	s_nop 3
	s_cmp_ge_u32 s2, 1
	s_cbranch_scc1 .Lmf1_done
	s_sleep 1
	s_add_u32 s3, s3, 1
	s_cmp_lt_u32 s3, 0x40000
	s_cbranch_scc1 .Lmf1_pl
.Lmf1_done:
	buffer_inv sc1
	s_waitcnt vmcnt(0)

.LBB0_549:
	s_waitcnt vmcnt(0)
	s_barrier
	s_waitcnt vmcnt(0)
	s_barrier
	s_mov_b64 s[0:1], exec
	v_readlane_b32 s2, v252, 22
	v_readlane_b32 s3, v252, 23
	v_readlane_b32 s44, v252, 50
	s_and_b64 s[2:3], s[0:1], s[2:3]
	v_readlane_b32 s45, v252, 51
	s_mov_b64 exec, s[2:3]
	s_cbranch_execz .LBB0_601
	v_mov_b32_e32 v4, 0x22000
	ds_read_b32 v5, v4
	ds_read_b32 v6, v4 offset:4
	v_readlane_b32 s3, v252, 21
	s_nop 3
	s_lshl_b32 s3, s3, 8
	s_add_i32 s3, s3, 0x80
	v_mov_b32_e32 v0, s3
	v_mov_b32_e32 v1, 1
	s_add_u32 s4, s60, 0x1400
	s_addc_u32 s5, s61, 0
	global_atomic_add v2, v0, v1, s[4:5] sc0
	s_add_u32 s4, s60, 0x2400
	s_addc_u32 s5, s61, 0
	s_waitcnt vmcnt(0) lgkmcnt(0)
	v_readfirstlane_b32 s2, v2
	v_readfirstlane_b32 s12, v5
	v_readfirstlane_b32 s13, v6
	s_nop 3
	s_mul_i32 s12, s12, 2
	s_mul_i32 s13, s13, 2
	s_add_i32 s2, s2, 1
	s_cmp_lg_u32 s2, s12
	s_cbranch_scc1 .Lmf2_poll
	buffer_wbl2 sc1
	s_waitcnt vmcnt(0)
	v_mov_b32_e32 v3, 0
	s_add_u32 s2, s60, 0x3480
	s_addc_u32 s3, s61, 0
	global_atomic_add v2, v3, v1, s[2:3] sc0
	s_waitcnt vmcnt(0)
	v_readfirstlane_b32 s2, v2
	s_nop 3
	s_add_i32 s2, s2, 1
	s_cmp_lg_u32 s2, s13
	s_cbranch_scc1 .Lmf2_poll
	v_mov_b32_e32 v3, 0x80
	global_atomic_add v3, v1, s[4:5]
	global_atomic_add v3, v1, s[4:5] offset:256
	global_atomic_add v3, v1, s[4:5] offset:512
	global_atomic_add v3, v1, s[4:5] offset:768
	global_atomic_add v3, v1, s[4:5] offset:1024
	global_atomic_add v3, v1, s[4:5] offset:1280
	global_atomic_add v3, v1, s[4:5] offset:1536
	global_atomic_add v3, v1, s[4:5] offset:1792
	global_atomic_add v3, v1, s[4:5] offset:2048
	global_atomic_add v3, v1, s[4:5] offset:2304
	global_atomic_add v3, v1, s[4:5] offset:2560
	global_atomic_add v3, v1, s[4:5] offset:2816
	global_atomic_add v3, v1, s[4:5] offset:3072
	global_atomic_add v3, v1, s[4:5] offset:3328
	global_atomic_add v3, v1, s[4:5] offset:3584
	global_atomic_add v3, v1, s[4:5] offset:3840

.Lmf2_pl:
	global_load_dword v2, v0, s[4:5] sc1
	s_waitcnt vmcnt(0)
	v_readfirstlane_b32 s2, v2
	s_nop 3
	s_cmp_ge_u32 s2, 2
	s_cbranch_scc1 .Lmf2_done
	s_sleep 1
	s_add_u32 s3, s3, 1
	s_cmp_lt_u32 s3, 0x40000
	s_cbranch_scc1 .Lmf2_pl

.LBB0_741:
	s_waitcnt vmcnt(0)
	v_readlane_b32 s74, v252, 22
	v_readlane_b32 s75, v252, 23
	s_waitcnt lgkmcnt(0)
	s_barrier
	s_and_saveexec_b64 s[0:1], s[74:75]
	v_readlane_b32 s68, v252, 29
	v_readlane_b32 s69, v252, 30
	v_readlane_b32 s78, v252, 26
	v_readlane_b32 s72, v252, 24
	v_readlane_b32 s76, v252, 36
	v_readlane_b32 s69, v252, 28
	v_readlane_b32 s79, v252, 27
	v_readlane_b32 s73, v252, 25
	v_readlane_b32 s77, v252, 37
	s_cbranch_execz .LBB0_793
	v_mov_b32_e32 v4, 0x22000
	ds_read_b32 v5, v4
	ds_read_b32 v6, v4 offset:4
	v_readlane_b32 s3, v252, 21
	s_nop 3
	s_lshl_b32 s3, s3, 8
	s_add_i32 s3, s3, 0x80
	v_mov_b32_e32 v0, s3
	v_mov_b32_e32 v1, 1
	s_add_u32 s4, s60, 0x1400
	s_addc_u32 s5, s61, 0
	global_atomic_add v2, v0, v1, s[4:5] sc0
	s_add_u32 s4, s60, 0x2400
	s_addc_u32 s5, s61, 0
	s_waitcnt vmcnt(0) lgkmcnt(0)
	v_readfirstlane_b32 s2, v2
	v_readfirstlane_b32 s12, v5
	v_readfirstlane_b32 s13, v6
	s_nop 3
	s_mul_i32 s12, s12, 3
	s_mul_i32 s13, s13, 3
	s_add_i32 s2, s2, 1
	s_cmp_lg_u32 s2, s12
	s_cbranch_scc1 .Lmf3_poll
	buffer_wbl2 sc1
	s_waitcnt vmcnt(0)
	v_mov_b32_e32 v3, 0
	s_add_u32 s2, s60, 0x3480
	s_addc_u32 s3, s61, 0
	global_atomic_add v2, v3, v1, s[2:3] sc0
	s_waitcnt vmcnt(0)
	v_readfirstlane_b32 s2, v2
	s_nop 3
	s_add_i32 s2, s2, 1
	s_cmp_lg_u32 s2, s13
	s_cbranch_scc1 .Lmf3_poll
	v_mov_b32_e32 v3, 0x80
	global_atomic_add v3, v1, s[4:5]
	global_atomic_add v3, v1, s[4:5] offset:256
	global_atomic_add v3, v1, s[4:5] offset:512
	global_atomic_add v3, v1, s[4:5] offset:768
	global_atomic_add v3, v1, s[4:5] offset:1024
	global_atomic_add v3, v1, s[4:5] offset:1280
	global_atomic_add v3, v1, s[4:5] offset:1536
	global_atomic_add v3, v1, s[4:5] offset:1792
	global_atomic_add v3, v1, s[4:5] offset:2048
	global_atomic_add v3, v1, s[4:5] offset:2304
	global_atomic_add v3, v1, s[4:5] offset:2560
	global_atomic_add v3, v1, s[4:5] offset:2816
	global_atomic_add v3, v1, s[4:5] offset:3072
	global_atomic_add v3, v1, s[4:5] offset:3328
	global_atomic_add v3, v1, s[4:5] offset:3584
	global_atomic_add v3, v1, s[4:5] offset:3840

.Lmf3_pl:
	global_load_dword v2, v0, s[4:5] sc1
	s_waitcnt vmcnt(0)
	v_readfirstlane_b32 s2, v2
	s_nop 3
	s_cmp_ge_u32 s2, 3
	s_cbranch_scc1 .Lmf3_done
	s_sleep 1
	s_add_u32 s3, s3, 1
	s_cmp_lt_u32 s3, 0x40000
	s_cbranch_scc1 .Lmf3_pl

.LBB0_842:
	s_waitcnt vmcnt(0)
	s_barrier
	s_and_saveexec_b64 s[0:1], s[74:75]
	s_cbranch_execz .LBB0_894
	v_mov_b32_e32 v4, 0x22000
	ds_read_b32 v5, v4
	ds_read_b32 v6, v4 offset:4
	v_readlane_b32 s3, v252, 21
	s_nop 3
	s_lshl_b32 s3, s3, 8
	s_add_i32 s3, s3, 0x80
	v_mov_b32_e32 v0, s3
	v_mov_b32_e32 v1, 1
	s_add_u32 s4, s60, 0x1400
	s_addc_u32 s5, s61, 0
	global_atomic_add v2, v0, v1, s[4:5] sc0
	s_add_u32 s4, s60, 0x2400
	s_addc_u32 s5, s61, 0
	s_waitcnt vmcnt(0) lgkmcnt(0)
	v_readfirstlane_b32 s2, v2
	v_readfirstlane_b32 s12, v5
	v_readfirstlane_b32 s13, v6
	s_nop 3
	s_mul_i32 s12, s12, 4
	s_mul_i32 s13, s13, 4
	s_add_i32 s2, s2, 1
	s_cmp_lg_u32 s2, s12
	s_cbranch_scc1 .Lmf4_poll
	buffer_wbl2 sc1
	s_waitcnt vmcnt(0)
	v_mov_b32_e32 v3, 0
	s_add_u32 s2, s60, 0x3480
	s_addc_u32 s3, s61, 0
	global_atomic_add v2, v3, v1, s[2:3] sc0
	s_waitcnt vmcnt(0)
	v_readfirstlane_b32 s2, v2
	s_nop 3
	s_add_i32 s2, s2, 1
	s_cmp_lg_u32 s2, s13
	s_cbranch_scc1 .Lmf4_poll
	v_mov_b32_e32 v3, 0x80
	global_atomic_add v3, v1, s[4:5]
	global_atomic_add v3, v1, s[4:5] offset:256
	global_atomic_add v3, v1, s[4:5] offset:512
	global_atomic_add v3, v1, s[4:5] offset:768
	global_atomic_add v3, v1, s[4:5] offset:1024
	global_atomic_add v3, v1, s[4:5] offset:1280
	global_atomic_add v3, v1, s[4:5] offset:1536
	global_atomic_add v3, v1, s[4:5] offset:1792
	global_atomic_add v3, v1, s[4:5] offset:2048
	global_atomic_add v3, v1, s[4:5] offset:2304
	global_atomic_add v3, v1, s[4:5] offset:2560
	global_atomic_add v3, v1, s[4:5] offset:2816
	global_atomic_add v3, v1, s[4:5] offset:3072
	global_atomic_add v3, v1, s[4:5] offset:3328
	global_atomic_add v3, v1, s[4:5] offset:3584
	global_atomic_add v3, v1, s[4:5] offset:3840

.Lmf4_pl:
	global_load_dword v2, v0, s[4:5] sc1
	s_waitcnt vmcnt(0)
	v_readfirstlane_b32 s2, v2
	s_nop 3
	s_cmp_ge_u32 s2, 4
	s_cbranch_scc1 .Lmf4_done
	s_sleep 1
	s_add_u32 s3, s3, 1
	s_cmp_lt_u32 s3, 0x40000
	s_cbranch_scc1 .Lmf4_pl

.LBB0_936:
	s_waitcnt vmcnt(0)
	s_waitcnt lgkmcnt(0)
	s_barrier
	s_and_saveexec_b64 s[0:1], s[74:75]
	s_cbranch_execz .LBB0_988
	v_mov_b32_e32 v4, 0x22000
	ds_read_b32 v5, v4
	ds_read_b32 v6, v4 offset:4
	v_readlane_b32 s3, v252, 21
	s_nop 3
	s_lshl_b32 s3, s3, 8
	s_add_i32 s3, s3, 0x80
	v_mov_b32_e32 v0, s3
	v_mov_b32_e32 v1, 1
	s_add_u32 s4, s60, 0x1400
	s_addc_u32 s5, s61, 0
	global_atomic_add v2, v0, v1, s[4:5] sc0
	s_add_u32 s4, s60, 0x2400
	s_addc_u32 s5, s61, 0
	s_waitcnt vmcnt(0) lgkmcnt(0)
	v_readfirstlane_b32 s2, v2
	v_readfirstlane_b32 s12, v5
	v_readfirstlane_b32 s13, v6
	s_nop 3
	s_mul_i32 s12, s12, 5
	s_mul_i32 s13, s13, 5
	s_add_i32 s2, s2, 1
	s_cmp_lg_u32 s2, s12
	s_cbranch_scc1 .Lmf5_poll
	buffer_wbl2 sc1
	s_waitcnt vmcnt(0)
	v_mov_b32_e32 v3, 0
	s_add_u32 s2, s60, 0x3480
	s_addc_u32 s3, s61, 0
	global_atomic_add v2, v3, v1, s[2:3] sc0
	s_waitcnt vmcnt(0)
	v_readfirstlane_b32 s2, v2
	s_nop 3
	s_add_i32 s2, s2, 1
	s_cmp_lg_u32 s2, s13
	s_cbranch_scc1 .Lmf5_poll
	v_mov_b32_e32 v3, 0x80
	global_atomic_add v3, v1, s[4:5]
	global_atomic_add v3, v1, s[4:5] offset:256
	global_atomic_add v3, v1, s[4:5] offset:512
	global_atomic_add v3, v1, s[4:5] offset:768
	global_atomic_add v3, v1, s[4:5] offset:1024
	global_atomic_add v3, v1, s[4:5] offset:1280
	global_atomic_add v3, v1, s[4:5] offset:1536
	global_atomic_add v3, v1, s[4:5] offset:1792
	global_atomic_add v3, v1, s[4:5] offset:2048
	global_atomic_add v3, v1, s[4:5] offset:2304
	global_atomic_add v3, v1, s[4:5] offset:2560
	global_atomic_add v3, v1, s[4:5] offset:2816
	global_atomic_add v3, v1, s[4:5] offset:3072
	global_atomic_add v3, v1, s[4:5] offset:3328
	global_atomic_add v3, v1, s[4:5] offset:3584
	global_atomic_add v3, v1, s[4:5] offset:3840

.Lmf5_pl:
	global_load_dword v2, v0, s[4:5] sc1
	s_waitcnt vmcnt(0)
	v_readfirstlane_b32 s2, v2
	s_nop 3
	s_cmp_ge_u32 s2, 5
	s_cbranch_scc1 .Lmf5_done
	s_sleep 1
	s_add_u32 s3, s3, 1
	s_cmp_lt_u32 s3, 0x40000
	s_cbranch_scc1 .Lmf5_pl

.LBB0_1012:
	s_waitcnt vmcnt(0)
	s_barrier
	s_and_saveexec_b64 s[0:1], s[74:75]
	s_cbranch_execz .LBB0_1064
	v_mov_b32_e32 v4, 0x22000
	ds_read_b32 v5, v4
	ds_read_b32 v6, v4 offset:4
	v_readlane_b32 s3, v252, 21
	s_nop 3
	s_lshl_b32 s3, s3, 8
	s_add_i32 s3, s3, 0x80
	v_mov_b32_e32 v0, s3
	v_mov_b32_e32 v1, 1
	s_add_u32 s4, s60, 0x1400
	s_addc_u32 s5, s61, 0
	global_atomic_add v2, v0, v1, s[4:5] sc0
	s_add_u32 s4, s60, 0x2400
	s_addc_u32 s5, s61, 0
	s_waitcnt vmcnt(0) lgkmcnt(0)
	v_readfirstlane_b32 s2, v2
	v_readfirstlane_b32 s12, v5
	v_readfirstlane_b32 s13, v6
	s_nop 3
	s_mul_i32 s12, s12, 6
	s_mul_i32 s13, s13, 6
	s_add_i32 s2, s2, 1
	s_cmp_lg_u32 s2, s12
	s_cbranch_scc1 .Lmf6_poll
	buffer_wbl2 sc1
	s_waitcnt vmcnt(0)
	v_mov_b32_e32 v3, 0
	s_add_u32 s2, s60, 0x3480
	s_addc_u32 s3, s61, 0
	global_atomic_add v2, v3, v1, s[2:3] sc0
	s_waitcnt vmcnt(0)
	v_readfirstlane_b32 s2, v2
	s_nop 3
	s_add_i32 s2, s2, 1
	s_cmp_lg_u32 s2, s13
	s_cbranch_scc1 .Lmf6_poll
	v_mov_b32_e32 v3, 0x80
	global_atomic_add v3, v1, s[4:5]
	global_atomic_add v3, v1, s[4:5] offset:256
	global_atomic_add v3, v1, s[4:5] offset:512
	global_atomic_add v3, v1, s[4:5] offset:768
	global_atomic_add v3, v1, s[4:5] offset:1024
	global_atomic_add v3, v1, s[4:5] offset:1280
	global_atomic_add v3, v1, s[4:5] offset:1536
	global_atomic_add v3, v1, s[4:5] offset:1792
	global_atomic_add v3, v1, s[4:5] offset:2048
	global_atomic_add v3, v1, s[4:5] offset:2304
	global_atomic_add v3, v1, s[4:5] offset:2560
	global_atomic_add v3, v1, s[4:5] offset:2816
	global_atomic_add v3, v1, s[4:5] offset:3072
	global_atomic_add v3, v1, s[4:5] offset:3328
	global_atomic_add v3, v1, s[4:5] offset:3584
	global_atomic_add v3, v1, s[4:5] offset:3840

.Lmf6_pl:
	global_load_dword v2, v0, s[4:5] sc1
	s_waitcnt vmcnt(0)
	v_readfirstlane_b32 s2, v2
	s_nop 3
	s_cmp_ge_u32 s2, 6
	s_cbranch_scc1 .Lmf6_done
	s_sleep 1
	s_add_u32 s3, s3, 1
	s_cmp_lt_u32 s3, 0x40000
	s_cbranch_scc1 .Lmf6_pl

.LBB0_1088:
	s_waitcnt vmcnt(0)
	s_barrier
	s_and_saveexec_b64 s[0:1], s[74:75]
	s_cbranch_execz .LBB0_1140
	v_mov_b32_e32 v4, 0x22000
	ds_read_b32 v5, v4
	ds_read_b32 v6, v4 offset:4
	v_readlane_b32 s3, v252, 21
	s_nop 3
	s_lshl_b32 s3, s3, 8
	s_add_i32 s3, s3, 0x80
	v_mov_b32_e32 v0, s3
	v_mov_b32_e32 v1, 1
	s_add_u32 s4, s60, 0x1400
	s_addc_u32 s5, s61, 0
	global_atomic_add v2, v0, v1, s[4:5] sc0
	s_add_u32 s4, s60, 0x2400
	s_addc_u32 s5, s61, 0
	s_waitcnt vmcnt(0) lgkmcnt(0)
	v_readfirstlane_b32 s2, v2
	v_readfirstlane_b32 s12, v5
	v_readfirstlane_b32 s13, v6
	s_nop 3
	s_mul_i32 s12, s12, 7
	s_mul_i32 s13, s13, 7
	s_add_i32 s2, s2, 1
	s_cmp_lg_u32 s2, s12
	s_cbranch_scc1 .Lmf7_poll
	buffer_wbl2 sc1
	s_waitcnt vmcnt(0)
	v_mov_b32_e32 v3, 0
	s_add_u32 s2, s60, 0x3480
	s_addc_u32 s3, s61, 0
	global_atomic_add v2, v3, v1, s[2:3] sc0
	s_waitcnt vmcnt(0)
	v_readfirstlane_b32 s2, v2
	s_nop 3
	s_add_i32 s2, s2, 1
	s_cmp_lg_u32 s2, s13
	s_cbranch_scc1 .Lmf7_poll
	v_mov_b32_e32 v3, 0x80
	global_atomic_add v3, v1, s[4:5]
	global_atomic_add v3, v1, s[4:5] offset:256
	global_atomic_add v3, v1, s[4:5] offset:512
	global_atomic_add v3, v1, s[4:5] offset:768
	global_atomic_add v3, v1, s[4:5] offset:1024
	global_atomic_add v3, v1, s[4:5] offset:1280
	global_atomic_add v3, v1, s[4:5] offset:1536
	global_atomic_add v3, v1, s[4:5] offset:1792
	global_atomic_add v3, v1, s[4:5] offset:2048
	global_atomic_add v3, v1, s[4:5] offset:2304
	global_atomic_add v3, v1, s[4:5] offset:2560
	global_atomic_add v3, v1, s[4:5] offset:2816
	global_atomic_add v3, v1, s[4:5] offset:3072
	global_atomic_add v3, v1, s[4:5] offset:3328
	global_atomic_add v3, v1, s[4:5] offset:3584
	global_atomic_add v3, v1, s[4:5] offset:3840

.Lmf7_pl:
	global_load_dword v2, v0, s[4:5] sc1
	s_waitcnt vmcnt(0)
	v_readfirstlane_b32 s2, v2
	s_nop 3
	s_cmp_ge_u32 s2, 7
	s_cbranch_scc1 .Lmf7_done
	s_sleep 1
	s_add_u32 s3, s3, 1
	s_cmp_lt_u32 s3, 0x40000
	s_cbranch_scc1 .Lmf7_pl
